# NSA selected branch fast path: next-iteration mask-probe prefetch issued between the interleaved staging writes and PV MFMAs
# speedup vs baseline: 1.0004x; 1.0004x over previous
; DI void nsa_item(const Params& p, int bk, int qb, char* smem, float Mb) {
;     ...
;             const unsigned sub = (unsigned)(m >> (wave * 16)) & 0xffffu;
;             if (sub) {
;                 const char* kb_ = tb + bsel * 18432 + fr * 144 + fq * 16;
;                 bf16x8 kf[4][2], vf[4][2];
; #pragma unroll
;                 for (int k4 = 0; k4 < 4; ++k4) {
;                     kf[k4][0] = *(const bf16x8*)(kb_ + k4 * 16 * 144); kf[k4][1] = *(const bf16x8*)(kb_ + k4 * 16 * 144 + 64);
;                     vf[k4][0] = *(const bf16x8*)(kb_ + 9216 + k4 * 16 * 144); vf[k4][1] = *(const bf16x8*)(kb_ + 9216 + k4 * 16 * 144 + 64);
;     ...
;             lstore(bsel ^ 1);
;             __syncthreads();
;             bsel ^= 1; j = jn; m = mn;
;         }
.Lsel_bot3:
	v_mov_b32_e32 v245, v242
	v_mov_b64_e32 v[88:89], v[208:209]
	s_waitcnt lgkmcnt(0)
	s_barrier
	s_andn2_b64 exec, exec, s[10:11]
	s_cbranch_execz .LBB0_559

; DI void nsa_item(const Params& p, int bk, int qb, char* smem, float Mb) {
;     ...
;                 for (int k4 = 0; k4 < 4; ++k4) {
;                     kf[k4][0] = *(const bf16x8*)(kb_ + k4 * 16 * 144); kf[k4][1] = *(const bf16x8*)(kb_ + k4 * 16 * 144 + 64);
;                     vf[k4][0] = *(const bf16x8*)(kb_ + 9216 + k4 * 16 * 144); vf[k4][1] = *(const bf16x8*)(kb_ + 9216 + k4 * 16 * 144 + 64);
;                 }
;                 const bool mine = (sub >> fr) & 1u;
;                 const float Ml = mine ? Mb : 3.0e38f;
;                 const bool diag = (j == cur);
; #pragma unroll
;                 for (int g = 0; g < 3; ++g) {
;                     f32x4 st[4];
;                     st_from(kf, qf[g], st, -Ml);
;                     if (diag) {
; #pragma unroll
;                         for (int k4 = 0; k4 < 4; ++k4)
; #pragma unroll
;                             for (int ii = 0; ii < 4; ++ii) {
;                                 const float pv = (j * 64 + k4 * 16 + fq * 4 + ii <= tq) ? __builtin_amdgcn_exp2f(st[k4][ii]) : 0.f;
;                                 st[k4][ii] = pv; ls[g] += pv;
;                             }
;                     } else {
; #pragma unroll
;                         for (int k4 = 0; k4 < 4; ++k4)
; #pragma unroll
;                             for (int ii = 0; ii < 4; ++ii) { const float pv = __builtin_amdgcn_exp2f(st[k4][ii]); st[k4][ii] = pv; ls[g] += pv; }
;                     }
;                     pv_from(vf, st, o[g]);
.Lsel_fast:
	ds_read_b128 v[140:143], v116 offset:6976
	ds_read_b128 v[108:111], v116 offset:9216
	ds_read_b128 v[88:91], v116 offset:9280
	ds_read_b128 v[92:95], v116 offset:11520
	ds_read_b128 v[96:99], v116 offset:11584
	ds_read_b128 v[100:103], v116 offset:13824
	ds_read_b128 v[104:107], v116 offset:13888
	ds_read_b128 v[112:115], v116 offset:16128
	s_waitcnt lgkmcnt(7)
	ds_read_b128 v[116:119], v116 offset:16192
	v_mfma_f32_16x16x32_bf16 v[156:159], v[120:123], v[0:3], v[124:127]
	v_mfma_f32_16x16x32_bf16 v[164:167], v[132:135], v[0:3], v[124:127]
	v_mfma_f32_16x16x32_bf16 v[172:175], v[144:147], v[0:3], v[124:127]
	v_mfma_f32_16x16x32_bf16 v[180:183], v[152:155], v[0:3], v[124:127]
	v_mfma_f32_16x16x32_bf16 v[156:159], v[128:131], v[4:7], v[156:159]
	v_mfma_f32_16x16x32_bf16 v[164:167], v[136:139], v[4:7], v[164:167]
	v_mfma_f32_16x16x32_bf16 v[172:175], v[148:151], v[4:7], v[172:175]
	v_mfma_f32_16x16x32_bf16 v[180:183], v[140:143], v[4:7], v[180:183]
	v_mfma_f32_16x16x32_bf16 v[184:187], v[120:123], v[8:11], v[124:127]
	v_mfma_f32_16x16x32_bf16 v[176:179], v[132:135], v[8:11], v[124:127]
	v_mfma_f32_16x16x32_bf16 v[168:171], v[144:147], v[8:11], v[124:127]
	v_mfma_f32_16x16x32_bf16 v[160:163], v[152:155], v[8:11], v[124:127]
	s_nop 1
	v_mfma_f32_16x16x32_bf16 v[184:187], v[128:131], v[12:15], v[184:187]
	v_exp_f32_e32 v156, v156
	v_exp_f32_e32 v157, v157
	v_exp_f32_e32 v158, v158
	v_exp_f32_e32 v159, v159
	v_mfma_f32_16x16x32_bf16 v[176:179], v[136:139], v[12:15], v[176:179]
	v_exp_f32_e32 v164, v164
	v_exp_f32_e32 v165, v165
	v_exp_f32_e32 v166, v166
	v_exp_f32_e32 v167, v167
	v_mfma_f32_16x16x32_bf16 v[168:171], v[148:151], v[12:15], v[168:171]
	v_exp_f32_e32 v172, v172
	v_exp_f32_e32 v173, v173
	v_exp_f32_e32 v174, v174
	v_exp_f32_e32 v175, v175
	v_mfma_f32_16x16x32_bf16 v[160:163], v[140:143], v[12:15], v[160:163]
	v_exp_f32_e32 v180, v180
	v_exp_f32_e32 v181, v181
	v_exp_f32_e32 v182, v182
	v_exp_f32_e32 v183, v183
	v_pk_add_f32 v[254:255], v[156:157], v[158:159]
	v_pk_add_f32 v[254:255], v[254:255], v[164:165]
	v_pk_add_f32 v[254:255], v[254:255], v[166:167]
	v_cvt_pk_bf16_f32 v156, v156, v157
	v_cvt_pk_bf16_f32 v157, v158, v159
	v_cvt_pk_bf16_f32 v158, v164, v165
	v_cvt_pk_bf16_f32 v159, v166, v167
	v_pk_add_f32 v[164:165], v[172:173], v[174:175]
	v_pk_add_f32 v[164:165], v[164:165], v[180:181]
	v_pk_add_f32 v[164:165], v[164:165], v[182:183]
	v_cvt_pk_bf16_f32 v172, v172, v173
	v_cvt_pk_bf16_f32 v173, v174, v175
	v_cvt_pk_bf16_f32 v174, v180, v181
	v_cvt_pk_bf16_f32 v175, v182, v183
	v_pk_add_f32 v[254:255], v[254:255], v[164:165]
	v_add_f32_e32 v244, v244, v254
	v_add_f32_e32 v244, v244, v255
	s_waitcnt lgkmcnt(0)
; DI void nsa_item(const Params& p, int bk, int qb, char* smem, float Mb) {
;     ...
;                 const unsigned long long mm = masks[j];
;                 const unsigned mlo = __builtin_amdgcn_readfirstlane((unsigned)mm), mhi = __builtin_amdgcn_readfirstlane((unsigned)(mm >> 32));
;     ...
;                 for (int g = 0; g < 3; ++g) {
;                     f32x4 st[4];
;                     st_from(kf, qf[g], st, -Ml);
;                     if (diag) {
; #pragma unroll
;                         for (int k4 = 0; k4 < 4; ++k4)
; #pragma unroll
;                             for (int ii = 0; ii < 4; ++ii) {
;                                 const float pv = (j * 64 + k4 * 16 + fq * 4 + ii <= tq) ? __builtin_amdgcn_exp2f(st[k4][ii]) : 0.f;
;                                 st[k4][ii] = pv; ls[g] += pv;
;                             }
;                     } else {
; #pragma unroll
;                         for (int k4 = 0; k4 < 4; ++k4)
; #pragma unroll
;                             for (int ii = 0; ii < 4; ++ii) { const float pv = __builtin_amdgcn_exp2f(st[k4][ii]); st[k4][ii] = pv; ls[g] += pv; }
;                     }
;                     pv_from(vf, st, o[g]);
;                 }
;             }
;             lstore(bsel ^ 1);
;             __syncthreads();
;             bsel ^= 1; j = jn; m = mn;
	s_nop 1
	v_mfma_f32_16x16x32_bf16 v[68:71], v[108:111], v[156:159], v[68:71]
	v_exp_f32_e32 v184, v184
	v_mfma_f32_16x16x32_bf16 v[64:67], v[92:95], v[156:159], v[64:67]
	v_exp_f32_e32 v185, v185
	v_mfma_f32_16x16x32_bf16 v[60:63], v[100:103], v[156:159], v[60:63]
	v_exp_f32_e32 v186, v186
	v_mfma_f32_16x16x32_bf16 v[56:59], v[112:115], v[156:159], v[56:59]
	v_exp_f32_e32 v187, v187
	v_mfma_f32_16x16x32_bf16 v[68:71], v[88:91], v[172:175], v[68:71]
	v_exp_f32_e32 v176, v176
	v_mfma_f32_16x16x32_bf16 v[64:67], v[96:99], v[172:175], v[64:67]
	v_exp_f32_e32 v177, v177
	v_mfma_f32_16x16x32_bf16 v[60:63], v[104:107], v[172:175], v[60:63]
	v_exp_f32_e32 v178, v178
	v_mfma_f32_16x16x32_bf16 v[56:59], v[116:119], v[172:175], v[56:59]
	v_exp_f32_e32 v179, v179
	v_mfma_f32_16x16x32_bf16 v[156:159], v[120:123], v[16:19], v[124:127]
	v_exp_f32_e32 v168, v168
	v_mfma_f32_16x16x32_bf16 v[164:167], v[132:135], v[16:19], v[124:127]
	v_exp_f32_e32 v169, v169
	v_mfma_f32_16x16x32_bf16 v[172:175], v[144:147], v[16:19], v[124:127]
	v_exp_f32_e32 v170, v170
	v_mfma_f32_16x16x32_bf16 v[180:183], v[152:155], v[16:19], v[124:127]
	v_exp_f32_e32 v171, v171
	v_mfma_f32_16x16x32_bf16 v[156:159], v[128:131], v[20:23], v[156:159]
	v_exp_f32_e32 v160, v160
	v_mfma_f32_16x16x32_bf16 v[164:167], v[136:139], v[20:23], v[164:167]
	v_exp_f32_e32 v161, v161
	v_mfma_f32_16x16x32_bf16 v[172:175], v[148:151], v[20:23], v[172:175]
	v_exp_f32_e32 v162, v162
	v_mfma_f32_16x16x32_bf16 v[180:183], v[140:143], v[20:23], v[180:183]
	v_exp_f32_e32 v163, v163
	v_pk_add_f32 v[254:255], v[184:185], v[186:187]
	v_pk_add_f32 v[254:255], v[254:255], v[176:177]
	v_pk_add_f32 v[254:255], v[254:255], v[178:179]
	v_cvt_pk_bf16_f32 v184, v184, v185
	v_cvt_pk_bf16_f32 v185, v186, v187
	v_cvt_pk_bf16_f32 v186, v176, v177
	v_cvt_pk_bf16_f32 v187, v178, v179
	v_pk_add_f32 v[176:177], v[168:169], v[170:171]
	v_pk_add_f32 v[176:177], v[176:177], v[160:161]
	v_pk_add_f32 v[176:177], v[176:177], v[162:163]
	v_cvt_pk_bf16_f32 v168, v168, v169
	v_cvt_pk_bf16_f32 v169, v170, v171
	v_cvt_pk_bf16_f32 v170, v160, v161
	v_cvt_pk_bf16_f32 v171, v162, v163
	v_pk_add_f32 v[254:255], v[254:255], v[176:177]
	v_add_f32_e32 v243, v243, v254
	v_add_f32_e32 v243, v243, v255
	s_nop 1
	v_mfma_f32_16x16x32_bf16 v[52:55], v[108:111], v[184:187], v[52:55]
	v_exp_f32_e32 v156, v156
	v_exp_f32_e32 v157, v157
	v_mfma_f32_16x16x32_bf16 v[48:51], v[92:95], v[184:187], v[48:51]
	v_exp_f32_e32 v158, v158
	v_exp_f32_e32 v159, v159
	v_mfma_f32_16x16x32_bf16 v[44:47], v[100:103], v[184:187], v[44:47]
	v_exp_f32_e32 v164, v164
	v_exp_f32_e32 v165, v165
	v_mfma_f32_16x16x32_bf16 v[40:43], v[112:115], v[184:187], v[40:43]
	v_exp_f32_e32 v166, v166
	v_exp_f32_e32 v167, v167
	v_mfma_f32_16x16x32_bf16 v[52:55], v[88:91], v[168:171], v[52:55]
	v_exp_f32_e32 v172, v172
	v_exp_f32_e32 v173, v173
	v_mfma_f32_16x16x32_bf16 v[48:51], v[96:99], v[168:171], v[48:51]
	v_exp_f32_e32 v174, v174
	v_exp_f32_e32 v175, v175
	v_mfma_f32_16x16x32_bf16 v[44:47], v[104:107], v[168:171], v[44:47]
	v_exp_f32_e32 v180, v180
	v_exp_f32_e32 v181, v181
	v_mfma_f32_16x16x32_bf16 v[40:43], v[116:119], v[168:171], v[40:43]
	v_exp_f32_e32 v182, v182
	v_exp_f32_e32 v183, v183
	v_pk_add_f32 v[254:255], v[156:157], v[158:159]
	v_pk_add_f32 v[254:255], v[254:255], v[164:165]
	v_pk_add_f32 v[254:255], v[254:255], v[166:167]
	v_cvt_pk_bf16_f32 v156, v156, v157
	v_cvt_pk_bf16_f32 v157, v158, v159
	v_cvt_pk_bf16_f32 v158, v164, v165
	v_cvt_pk_bf16_f32 v159, v166, v167
	v_pk_add_f32 v[164:165], v[172:173], v[174:175]
	v_pk_add_f32 v[164:165], v[164:165], v[180:181]
	v_pk_add_f32 v[164:165], v[164:165], v[182:183]
	v_cvt_pk_bf16_f32 v172, v172, v173
	v_cvt_pk_bf16_f32 v173, v174, v175
	v_cvt_pk_bf16_f32 v174, v180, v181
	v_cvt_pk_bf16_f32 v175, v182, v183
	v_pk_add_f32 v[254:255], v[254:255], v[164:165]
	v_add_f32_e32 v241, v241, v254
	v_add_f32_e32 v241, v241, v255
	s_or_b64 exec, exec, s[12:13]
	s_and_b64 s[4:5], exec, s[4:5]
	s_or_b64 s[10:11], s[4:5], s[10:11]
	s_xor_b32 s22, s22, 1
	s_mul_i32 s4, s22, 0x4800
	v_add_u32_e32 v254, s4, v195
	v_readlane_b32 s2, v249, 29
	s_waitcnt vmcnt(3)
	ds_write_b128 v254, v[72:75]
	v_mfma_f32_16x16x32_bf16 v[36:39], v[108:111], v[156:159], v[36:39]
	v_mfma_f32_16x16x32_bf16 v[32:35], v[92:95], v[156:159], v[32:35]
	s_waitcnt vmcnt(2)
	ds_write_b128 v254, v[76:79] offset:4608
	v_lshl_add_u32 v72, v242, 3, s2
	ds_read_b64 v[72:73], v72
	v_mfma_f32_16x16x32_bf16 v[28:31], v[100:103], v[156:159], v[28:31]
	v_mfma_f32_16x16x32_bf16 v[24:27], v[112:115], v[156:159], v[24:27]
	s_waitcnt vmcnt(1)
	ds_write_b128 v254, v[80:83] offset:9216
	v_mfma_f32_16x16x32_bf16 v[36:39], v[88:91], v[172:175], v[36:39]
	v_mfma_f32_16x16x32_bf16 v[32:35], v[96:99], v[172:175], v[32:35]
	s_waitcnt vmcnt(0)
	ds_write_b128 v254, v[84:87] offset:13824
	v_mfma_f32_16x16x32_bf16 v[28:31], v[104:107], v[172:175], v[28:31]
	v_mfma_f32_16x16x32_bf16 v[24:27], v[116:119], v[172:175], v[24:27]
	s_branch .Lsel_bot3
